# P5 sample-row loop: all four g_fin pieces loaded up front (no store drains between them)
# speedup vs baseline: 1.0088x; 1.0024x over previous
.LBB0_1334:
	global_load_dwordx4 v[12:15], v[2:3], off offset:-3072
	global_load_dwordx4 v[16:19], v[2:3], off offset:-2048
	global_load_dwordx4 v[20:23], v[2:3], off
	global_load_dwordx4 v[24:27], v[2:3], off offset:-1024
	global_load_dwordx4 v[28:31], v[0:1], off
	global_load_dwordx4 v[50:53], v[0:1], off offset:1024
	global_load_dwordx4 v[54:57], v[0:1], off offset:2048
	global_load_dwordx4 v[58:61], v[0:1], off offset:3072
	s_add_i32 s2, s2, s50
	s_cmp_lt_i32 s2, 0x8100
	s_waitcnt vmcnt(7)
	v_pk_mul_f32 v[32:33], v[14:15], v[14:15]
	v_pk_mul_f32 v[34:35], v[12:13], v[12:13]
	s_waitcnt vmcnt(6)
	v_pk_mul_f32 v[36:37], v[18:19], v[18:19]
	v_pk_mul_f32 v[38:39], v[16:17], v[16:17]
	v_pk_mov_b32 v[44:45], v[34:35], v[32:33] op_sel:[1,0]
	v_mov_b32_e32 v35, v33
	v_pk_mov_b32 v[32:33], v[38:39], v[36:37] op_sel:[1,0]
	v_mov_b32_e32 v39, v37
	s_waitcnt vmcnt(5)
	v_mul_f32_e32 v43, v20, v20
	s_waitcnt vmcnt(4)
	v_mul_f32_e32 v40, v25, v25
	v_mul_f32_e32 v42, v27, v27
	v_pk_add_f32 v[34:35], v[44:45], v[34:35]
	v_pk_add_f32 v[32:33], v[32:33], v[38:39]
	v_mul_f32_e32 v46, v21, v21
	v_mul_f32_e32 v47, v22, v22
	v_mul_f32_e32 v48, v23, v23
	v_pk_fma_f32 v[36:37], v[24:25], v[24:25], v[40:41] op_sel_hi:[1,1,0]
	v_pk_fma_f32 v[40:41], v[26:27], v[26:27], v[42:43] op_sel_hi:[1,1,0]
	v_pk_add_f32 v[34:35], v[34:35], v[34:35] op_sel:[0,1] op_sel_hi:[1,0]
	v_pk_add_f32 v[32:33], v[32:33], v[32:33] op_sel:[0,1] op_sel_hi:[1,0]
	v_mov_b32_e32 v37, v47
	v_mov_b32_e32 v41, v48
	v_mov_b32_e32 v35, v43
	v_mov_b32_e32 v33, v46
	v_pk_add_f32 v[36:37], v[36:37], v[40:41]
	v_pk_add_f32 v[32:33], v[34:35], v[32:33]
	s_nop 0
	v_pk_add_f32 v[32:33], v[32:33], v[36:37]
	s_nop 0
	v_add_f32_e32 v32, v32, v33
	ds_bpermute_b32 v33, v4, v32
	s_waitcnt lgkmcnt(0)
	v_add_f32_e32 v32, v32, v33
	ds_bpermute_b32 v33, v5, v32
	s_waitcnt lgkmcnt(0)
	v_add_f32_e32 v32, v32, v33
	ds_bpermute_b32 v33, v6, v32
	s_waitcnt lgkmcnt(0)
	v_add_f32_e32 v32, v32, v33
	ds_bpermute_b32 v33, v7, v32
	s_waitcnt lgkmcnt(0)
	v_add_f32_e32 v32, v32, v33
	ds_bpermute_b32 v33, v8, v32
	s_waitcnt lgkmcnt(0)
	v_add_f32_e32 v32, v32, v33
	ds_bpermute_b32 v33, v9, v32
	s_waitcnt lgkmcnt(0)
	v_add_f32_e32 v32, v32, v33
	v_fmamk_f32 v32, v32, 0x3a800000, v10
	v_mul_f32_e32 v33, 0x4f800000, v32
	v_cmp_gt_f32_e32 vcc, s3, v32
	s_nop 1
	v_cndmask_b32_e32 v32, v32, v33, vcc
	v_sqrt_f32_e32 v33, v32
	s_nop 0
	v_add_u32_e32 v34, -1, v33
	v_add_u32_e32 v35, 1, v33
	v_fma_f32 v36, -v34, v33, v32
	v_fma_f32 v37, -v35, v33, v32
	v_cmp_ge_f32_e64 s[0:1], 0, v36
	s_nop 1
	v_cndmask_b32_e64 v33, v33, v34, s[0:1]
	v_cmp_lt_f32_e64 s[0:1], 0, v37
	s_nop 1
	v_cndmask_b32_e64 v33, v33, v35, s[0:1]
	v_mul_f32_e32 v34, 0x37800000, v33
	v_cndmask_b32_e32 v33, v33, v34, vcc
	v_cmp_class_f32_e32 vcc, v32, v11
	s_nop 1
	v_cndmask_b32_e32 v32, v33, v32, vcc
	v_div_scale_f32 v33, s[0:1], v32, v32, 1.0
	v_rcp_f32_e32 v34, v33
	v_div_scale_f32 v35, vcc, 1.0, v32, 1.0
	v_fma_f32 v36, -v33, v34, 1.0
	v_fmac_f32_e32 v34, v36, v34
	v_mul_f32_e32 v36, v35, v34
	v_fma_f32 v37, -v33, v36, v35
	v_fmac_f32_e32 v36, v37, v34
	v_fma_f32 v33, -v33, v36, v35
	v_div_fmas_f32 v33, v33, v34, v36
	v_div_fixup_f32 v32, v33, v32, 1.0
	v_pk_mul_f32 v[12:13], v[32:33], v[12:13] op_sel_hi:[0,1]
	v_pk_mul_f32 v[14:15], v[32:33], v[14:15] op_sel_hi:[0,1]
	s_waitcnt vmcnt(0)
	v_pk_mul_f32 v[14:15], v[14:15], v[30:31]
	v_pk_mul_f32 v[12:13], v[12:13], v[28:29]
	global_store_dwordx4 v[2:3], v[12:15], off offset:-3072
	v_pk_mul_f32 v[18:19], v[32:33], v[18:19] op_sel_hi:[0,1]
	v_pk_mul_f32 v[16:17], v[32:33], v[16:17] op_sel_hi:[0,1]
	v_pk_mul_f32 v[12:13], v[16:17], v[50:51]
	v_pk_mul_f32 v[14:15], v[18:19], v[52:53]
	global_store_dwordx4 v[2:3], v[12:15], off offset:-2048
	v_pk_mul_f32 v[16:17], v[32:33], v[26:27] op_sel_hi:[0,1]
	v_pk_mul_f32 v[18:19], v[32:33], v[24:25] op_sel_hi:[0,1]
	v_pk_mul_f32 v[12:13], v[18:19], v[54:55]
	v_pk_mul_f32 v[14:15], v[16:17], v[56:57]
	global_store_dwordx4 v[2:3], v[12:15], off offset:-1024
	v_pk_mul_f32 v[16:17], v[32:33], v[22:23] op_sel_hi:[0,1]
	v_pk_mul_f32 v[18:19], v[32:33], v[20:21] op_sel_hi:[0,1]
	v_pk_mul_f32 v[12:13], v[18:19], v[58:59]
	v_pk_mul_f32 v[14:15], v[16:17], v[60:61]
	global_store_dwordx4 v[2:3], v[12:15], off
	v_lshl_add_u64 v[2:3], v[2:3], 0, s[4:5]
	s_cbranch_scc1 .LBB0_1334
